# attention loop: row-max tree, rescale decision and part of softmax-start moved into PV MFMA gaps; PV-start vmcnt(0) removed
# speedup vs baseline: 1.0063x; 1.0063x over previous
.LBB0_755:
	ds_read_b64_tr_b16 v[150:151], v167
	ds_read_b64_tr_b16 v[152:153], v167 offset:2048
	ds_read_b64_tr_b16 v[154:155], v167 offset:4096
	ds_read_b64_tr_b16 v[156:157], v167 offset:6144
	ds_read_b64_tr_b16 v[158:159], v167 offset:8192
	ds_read_b64_tr_b16 v[160:161], v167 offset:10240
	ds_read_b64_tr_b16 v[204:205], v167 offset:12288
	ds_read_b64_tr_b16 v[206:207], v167 offset:14336
	v_max_f32_e32 v1, v85, v85
	v_max_f32_e32 v100, v84, v84
	v_max_f32_e32 v1, v100, v1
	v_max3_f32 v100, v86, v87, v69
	v_max3_f32 v1, v1, v68, v70
	v_max3_f32 v1, v1, v71, v88
	v_max3_f32 v100, v100, v90, v91
	v_max3_f32 v1, v1, v89, v72
	v_max3_f32 v100, v100, v74, v75
	s_waitcnt lgkmcnt(6)
	v_mfma_f32_32x32x16_bf16 v[4:19], v[130:133], v[150:153], v[4:19]
	ds_read_b64_tr_b16 v[208:209], v167 offset:512
	ds_read_b64_tr_b16 v[210:211], v167 offset:2560
	v_max3_f32 v1, v1, v73, v92
	v_max3_f32 v100, v100, v94, v95
	v_max3_f32 v1, v1, v93, v76
	s_waitcnt lgkmcnt(6)
	v_mfma_f32_32x32x16_bf16 v[4:19], v[108:111], v[154:157], v[4:19]
	ds_read_b64_tr_b16 v[150:151], v167 offset:4608
	ds_read_b64_tr_b16 v[152:153], v167 offset:6656
	v_max3_f32 v100, v100, v78, v79
	v_max3_f32 v1, v1, v77, v96
	v_max3_f32 v100, v100, v98, v99
	s_waitcnt lgkmcnt(6)
	v_mfma_f32_32x32x16_bf16 v[4:19], v[102:105], v[158:161], v[4:19]
	ds_read_b64_tr_b16 v[154:155], v167 offset:8704
	ds_read_b64_tr_b16 v[156:157], v167 offset:10752
	v_max3_f32 v1, v1, v97, v80
	v_max3_f32 v100, v100, v82, v83
	v_max3_f32 v1, v1, v81, v100
	s_waitcnt lgkmcnt(6)
	v_mfma_f32_32x32x16_bf16 v[4:19], v[134:137], v[204:207], v[4:19]
	ds_read_b64_tr_b16 v[158:159], v167 offset:12800
	ds_read_b64_tr_b16 v[160:161], v167 offset:14848
	v_mov_b32_e32 v100, v1
	s_waitcnt lgkmcnt(6)
	v_mfma_f32_32x32x16_bf16 v[52:67], v[130:133], v[208:211], v[52:67]
	ds_read_b64_tr_b16 v[204:205], v167 offset:1024
	ds_read_b64_tr_b16 v[206:207], v167 offset:3072
	v_permlane32_swap_b32_e32 v1, v100
	v_max_f32_e32 v100, v100, v100
	v_max_f32_e32 v1, v1, v1
	v_max_f32_e32 v1, v1, v100
	s_waitcnt lgkmcnt(6)
	v_mfma_f32_32x32x16_bf16 v[52:67], v[108:111], v[150:153], v[52:67]
	ds_read_b64_tr_b16 v[208:209], v167 offset:5120
	ds_read_b64_tr_b16 v[210:211], v167 offset:7168
	v_sub_f32_e32 v100, v1, v140
	v_cmp_ge_f32_e32 vcc, s3, v100
	s_cmp_eq_u64 vcc, exec
	v_mov_b32_e32 v203, 1.0
	s_cbranch_scc0 .LBB0_768
.Lattn_back_a:
	s_waitcnt lgkmcnt(6)
	v_mfma_f32_32x32x16_bf16 v[52:67], v[102:105], v[154:157], v[52:67]
	ds_read_b64_tr_b16 v[150:151], v167 offset:9216
	ds_read_b64_tr_b16 v[152:153], v167 offset:11264
	v_sub_f32_e32 v249, v84, v140
	v_sub_f32_e32 v84, v85, v140
	v_sub_f32_e32 v85, v86, v140
	v_sub_f32_e32 v86, v87, v140
	s_waitcnt lgkmcnt(6)
	v_mfma_f32_32x32x16_bf16 v[52:67], v[134:137], v[158:161], v[52:67]
	ds_read_b64_tr_b16 v[154:155], v167 offset:13312
	ds_read_b64_tr_b16 v[156:157], v167 offset:15360
	v_sub_f32_e32 v87, v88, v140
	v_sub_f32_e32 v88, v89, v140
	v_sub_f32_e32 v89, v90, v140
	v_sub_f32_e32 v90, v91, v140
	s_waitcnt lgkmcnt(6)
	v_mfma_f32_32x32x16_bf16 v[36:51], v[130:133], v[204:207], v[36:51]
	ds_read_b64_tr_b16 v[158:159], v167 offset:1536
	ds_read_b64_tr_b16 v[160:161], v167 offset:3584
	v_sub_f32_e32 v91, v92, v140
	v_sub_f32_e32 v92, v93, v140
	v_sub_f32_e32 v93, v94, v140
	v_sub_f32_e32 v94, v95, v140
	s_waitcnt lgkmcnt(6)
	v_mfma_f32_32x32x16_bf16 v[36:51], v[108:111], v[208:211], v[36:51]
	ds_read_b64_tr_b16 v[204:205], v167 offset:5632
	ds_read_b64_tr_b16 v[206:207], v167 offset:7680
	v_sub_f32_e32 v95, v96, v140
	v_sub_f32_e32 v96, v97, v140
	v_sub_f32_e32 v97, v98, v140
	v_sub_f32_e32 v98, v99, v140
	s_waitcnt lgkmcnt(6)
	v_mfma_f32_32x32x16_bf16 v[36:51], v[102:105], v[150:153], v[36:51]
	ds_read_b64_tr_b16 v[208:209], v167 offset:9728
	ds_read_b64_tr_b16 v[210:211], v167 offset:11776
	v_sub_f32_e32 v99, v68, v140
	v_sub_f32_e32 v216, v76, v140
	v_sub_f32_e32 v217, v77, v140
	v_sub_f32_e32 v218, v78, v140
	s_waitcnt lgkmcnt(6)
	v_mfma_f32_32x32x16_bf16 v[36:51], v[134:137], v[154:157], v[36:51]
	ds_read_b64_tr_b16 v[150:151], v167 offset:13824
	ds_read_b64_tr_b16 v[152:153], v167 offset:15872
	v_sub_f32_e32 v219, v79, v140
	v_sub_f32_e32 v220, v80, v140
	v_sub_f32_e32 v221, v81, v140
	v_sub_f32_e32 v222, v82, v140
	s_waitcnt lgkmcnt(6)
	v_mfma_f32_32x32x16_bf16 v[20:35], v[130:133], v[158:161], v[20:35]
	v_sub_f32_e32 v223, v83, v140
	v_exp_f32_e32 v212, v95
	s_waitcnt lgkmcnt(4)
	v_mfma_f32_32x32x16_bf16 v[20:35], v[108:111], v[204:207], v[20:35]
	v_exp_f32_e32 v213, v96
	v_exp_f32_e32 v214, v97
	s_waitcnt lgkmcnt(2)
	v_mfma_f32_32x32x16_bf16 v[20:35], v[102:105], v[208:211], v[20:35]
	v_exp_f32_e32 v215, v98
	s_waitcnt lgkmcnt(0)
	v_mfma_f32_32x32x16_bf16 v[20:35], v[134:137], v[150:153], v[20:35]
	v_cmp_gt_f32_e32 vcc, 1.0, v203
	s_cbranch_vccz .LBB0_759
	s_and_saveexec_b64 s[54:55], s[0:1]
	ds_write_b32 v166, v203 offset:128
	s_or_b64 exec, exec, s[54:55]
	s_waitcnt lgkmcnt(0)
	v_add_u32_e32 v1, s57, v165
	ds_read_b128 v[100:103], v1 offset:224
	ds_read_b128 v[104:107], v1 offset:192
	ds_read_b128 v[108:111], v1 offset:160
	ds_read_b128 v[130:133], v1 offset:128
	s_waitcnt lgkmcnt(3)
	v_pk_mul_f32 v[16:17], v[16:17], v[100:101]
	s_waitcnt lgkmcnt(2)
	v_pk_mul_f32 v[12:13], v[12:13], v[104:105]
	s_waitcnt lgkmcnt(1)
	v_pk_mul_f32 v[8:9], v[8:9], v[108:109]
	v_pk_mul_f32 v[18:19], v[18:19], v[102:103]
	v_pk_mul_f32 v[14:15], v[14:15], v[106:107]
	v_pk_mul_f32 v[10:11], v[10:11], v[110:111]
	s_waitcnt lgkmcnt(0)
	v_pk_mul_f32 v[6:7], v[6:7], v[132:133]
	v_pk_mul_f32 v[4:5], v[4:5], v[130:131]
	v_pk_mul_f32 v[64:65], v[64:65], v[100:101]
	v_pk_mul_f32 v[60:61], v[60:61], v[104:105]
	v_pk_mul_f32 v[56:57], v[56:57], v[108:109]
	v_pk_mul_f32 v[66:67], v[66:67], v[102:103]
	v_pk_mul_f32 v[62:63], v[62:63], v[106:107]
	v_pk_mul_f32 v[58:59], v[58:59], v[110:111]
	v_pk_mul_f32 v[54:55], v[54:55], v[132:133]
	v_pk_mul_f32 v[52:53], v[52:53], v[130:131]
	v_pk_mul_f32 v[48:49], v[48:49], v[100:101]
	v_pk_mul_f32 v[44:45], v[44:45], v[104:105]
	v_pk_mul_f32 v[40:41], v[40:41], v[108:109]
	v_pk_mul_f32 v[50:51], v[50:51], v[102:103]
	v_pk_mul_f32 v[46:47], v[46:47], v[106:107]
	v_pk_mul_f32 v[42:43], v[42:43], v[110:111]
	v_pk_mul_f32 v[38:39], v[38:39], v[132:133]
	v_pk_mul_f32 v[36:37], v[36:37], v[130:131]
	v_pk_mul_f32 v[32:33], v[32:33], v[100:101]
	v_pk_mul_f32 v[28:29], v[28:29], v[104:105]
	v_pk_mul_f32 v[24:25], v[24:25], v[108:109]
	v_pk_mul_f32 v[34:35], v[34:35], v[102:103]
	v_pk_mul_f32 v[30:31], v[30:31], v[106:107]
	v_pk_mul_f32 v[26:27], v[26:27], v[110:111]
	v_pk_mul_f32 v[22:23], v[22:23], v[132:133]
	v_pk_mul_f32 v[20:21], v[20:21], v[130:131]
; #define LAS __attribute__((address_space(3)))
; __device__ __forceinline__ int v_rd_base(int lane) { return ((lane & 3) << 3) | (((lane >> 2) & 3) << 6) | (((lane >> 4) & 1) << 5) | (((lane >> 5) & 1) << 8); }
; template <int G> __device__ __forceinline__ void fin_gap(f32x16& P0, f32x16& P1, float (&sacc)[4], unsigned (&cv)[16], u32x4 (&pw)[4]) {
;   if constexpr (G < 16) { P1[G] = __builtin_amdgcn_exp2f(P1[G]); sacc[G & 3] += P0[G]; }
;   else { constexpr int r = 2 * (G - 16); sacc[r & 3] += P1[r]; sacc[(r + 1) & 3] += P1[r + 1]; }
;   if constexpr (G < 4) cv[G] = cvtpk_c(P0[2 * G], P0[2 * G + 1]);
;   else if constexpr (G >= 6 && G < 10) { constexpr int i = G - 2; cv[i] = cvtpk_c(P0[2 * i], P0[2 * i + 1]); }
;   else if constexpr (G >= 12 && G < 16) { constexpr int i = G - 4, j = i - 8; cv[i] = cvtpk_c(P1[2 * j], P1[2 * j + 1]); }
;   else if constexpr (G >= 18 && G < 22) { constexpr int i = G - 6, j = i - 8; cv[i] = cvtpk_c(P1[2 * j], P1[2 * j + 1]); }
;   if constexpr (G == 4 || G == 10 || G == 16 || G == 22) { constexpr int q = (G - 4) / 6; auto r0 = __builtin_amdgcn_permlane32_swap(cv[4 * q], cv[4 * q + 2], false, false); pw[q].x = r0[0]; pw[q].z = r0[1]; }
;   if constexpr (G == 5 || G == 11 || G == 17 || G == 23) { constexpr int q = (G - 5) / 6; auto r1 = __builtin_amdgcn_permlane32_swap(cv[4 * q + 1], cv[4 * q + 3], false, false); pw[q].y = r1[0]; pw[q].w = r1[1]; }
; }
; template <int ABL> __device__ __forceinline__ void attn_unit(int b, int h, int qb, const bf16_t* Q, const bf16_t* KV, const bf16_t* KPE, bf16_t* MG, float* ssqa, LAS unsigned char* L) {
;     ...
;   DMA_K(0, 0); DMA_V(0, 0); DMA_K(1, 1);
;   const bf16_t* Qw = Q + (rowbase + q0 + wid * QBLK + r32) * LDQ + h * 192 + hi * 8;
; #pragma unroll
;   for (int d0 = 0; d0 < 4; ++d0) qr[d0] = ld8(Qw + d0 * 16);
; #pragma unroll
;   for (int dd = 0; dd < 8; ++dd) *reinterpret_cast<LAS bf16x8*>(Qr + (dd >> 2) * 4096 + kro + (((2 * (dd & 3) + hi) ^ ksw) << 4)) = ld8(Qw + (4 + dd) * 16);
;   const int vb0 = (int)(unsigned)(uintptr_t)Vl + v_rd_base(lane);
;     ...
;   f32x16 pA0, pA1, pB0, pB1; float mnA, mnB, alA, alB; constexpr int NT = SEQ / KVBLK;
;   const LAS unsigned char* Vp = Vl + v_rd_base(lane);
;   u32x4 pw[4]; unsigned cv[16]; float sacc[4];
.LBB0_759:
	v_lshl_add_u64 v[112:113], s[28:29], 0, v[146:147]
	s_mov_b64 s[54:55], 0x18fc0000
	s_mov_b32 m0, s78
	v_lshl_add_u64 v[100:101], v[112:113], 0, s[54:55]
	s_waitcnt vmcnt(0)
	s_barrier
	global_load_lds_dwordx4 v[100:101], off
	v_lshl_add_u64 v[100:101], v[112:113], 0, s[38:39]
	s_add_i32 m0, s78, 0x2000
	v_lshl_add_u64 v[136:137], s[28:29], 0, v[144:145]
	global_load_lds_dwordx4 v[100:101], off
	v_lshl_add_u64 v[100:101], v[136:137], 0, s[40:41]
	s_add_i32 m0, s78, 0x4000
	v_lshl_add_u64 v[134:135], s[28:29], 0, v[148:149]
	global_load_lds_dwordx4 v[100:101], off
	v_lshl_add_u64 v[100:101], v[134:135], 0, s[42:43]
	s_mov_b32 m0, s58
	global_load_lds_dwordx4 v[100:101], off
	v_lshl_add_u64 v[100:101], v[134:135], 0, s[44:45]
	s_mov_b32 m0, s77
	global_load_lds_dwordx4 v[100:101], off
	v_exp_f32_e32 v1, v249
	v_exp_f32_e32 v101, v84
	v_exp_f32_e32 v103, v85
	v_exp_f32_e32 v205, v89
	v_exp_f32_e32 v206, v90
	v_sub_f32_e32 v102, v70, v140
	v_sub_f32_e32 v204, v74, v140
	v_exp_f32_e32 v160, v88
	v_sub_f32_e32 v88, v69, v140
	v_sub_f32_e32 v158, v72, v140
	v_exp_f32_e32 v154, v86
	v_exp_f32_e32 v159, v87
	v_exp_f32_e32 v208, v91
	v_exp_f32_e32 v209, v92
	v_exp_f32_e32 v210, v93
	v_exp_f32_e32 v211, v94
	v_sub_f32_e32 v155, v71, v140
	v_sub_f32_e32 v161, v73, v140
	v_sub_f32_e32 v207, v75, v140
	ds_read_b128 v[68:71], v178 offset:32768
	ds_read_b128 v[84:87], v178 offset:36864
	s_waitcnt lgkmcnt(0)
	v_mfma_f32_32x32x16_bf16 v[68:83], v[68:71], v[126:129], 0
	ds_read_b128 v[104:107], v179 offset:32768
	ds_read_b128 v[108:111], v179 offset:36864
	v_cvt_pk_bf16_f32 v100, v1, v101
	v_exp_f32_e32 v226, v99
	v_add_f32_e32 v227, 0, v1
	v_exp_f32_e32 v1, v88
	v_mfma_f32_32x32x16_bf16 v[84:99], v[84:87], v[126:129], 0
	v_add_f32_e32 v228, 0, v101
	v_cvt_pk_bf16_f32 v101, v103, v154
	s_waitcnt lgkmcnt(0)
	v_mfma_f32_32x32x16_bf16 v[68:83], v[104:107], v[122:125], v[68:83]
	ds_read_b128 v[130:133], v177 offset:32768
	ds_read_b128 v[150:153], v177 offset:36864
	v_exp_f32_e32 v229, v102
	v_cvt_pk_bf16_f32 v102, v159, v160
	v_add_f32_e32 v230, 0, v103
	v_mfma_f32_32x32x16_bf16 v[84:99], v[108:111], v[122:125], v[84:99]
	v_add_f32_e32 v105, 0, v154
	v_cvt_pk_bf16_f32 v103, v205, v206
	v_exp_f32_e32 v231, v155
	s_waitcnt lgkmcnt(0)
	v_mfma_f32_32x32x16_bf16 v[68:83], v[130:133], v[118:121], v[68:83]
	ds_read_b128 v[106:109], v176 offset:32768
	ds_read_b128 v[154:157], v176 offset:36864
	v_permlane32_swap_b32_e32 v100, v102
	v_exp_f32_e32 v232, v158
	v_add_f32_e32 v227, v159, v227
	v_mfma_f32_32x32x16_bf16 v[84:99], v[150:153], v[118:121], v[84:99]
	v_permlane32_swap_b32_e32 v101, v103
	v_exp_f32_e32 v233, v161
	v_add_f32_e32 v228, v160, v228
	s_waitcnt lgkmcnt(0)
	v_mfma_f32_32x32x16_bf16 v[68:83], v[106:109], v[114:117], v[68:83]
	ds_read_b128 v[130:133], v178 offset:40960
	ds_read_b128 v[150:153], v178 offset:45056
	ds_read_b128 v[158:161], v171
	v_cvt_pk_bf16_f32 v104, v208, v209
	v_exp_f32_e32 v234, v204
	v_add_f32_e32 v230, v205, v230
	v_mfma_f32_32x32x16_bf16 v[84:99], v[154:157], v[114:117], v[84:99]
	v_add_f32_e32 v236, v206, v105
	v_cvt_pk_bf16_f32 v105, v210, v211
	v_exp_f32_e32 v235, v207
	s_waitcnt lgkmcnt(0)
	v_mfma_f32_32x32x16_bf16 v[68:83], v[130:133], v[158:161], v[68:83]
	ds_read_b128 v[108:111], v179 offset:40960
	ds_read_b128 v[154:157], v179 offset:45056
	ds_read_b128 v[204:207], v170
	v_cvt_pk_bf16_f32 v106, v212, v213
	v_exp_f32_e32 v216, v216
	v_add_f32_e32 v227, v208, v227
	v_mfma_f32_32x32x16_bf16 v[84:99], v[150:153], v[158:161], v[84:99]
	v_cvt_pk_bf16_f32 v107, v214, v215
	v_exp_f32_e32 v217, v217
	v_add_f32_e32 v228, v209, v228
	s_waitcnt lgkmcnt(0)
	v_mfma_f32_32x32x16_bf16 v[68:83], v[108:111], v[204:207], v[68:83]
	ds_read_b128 v[130:133], v177 offset:40960
	ds_read_b128 v[150:153], v177 offset:45056
	ds_read_b128 v[158:161], v169
	v_permlane32_swap_b32_e32 v104, v106
	v_exp_f32_e32 v218, v218
	v_add_f32_e32 v230, v210, v230
	v_mfma_f32_32x32x16_bf16 v[84:99], v[154:157], v[204:207], v[84:99]
	v_add_f32_e32 v111, v211, v236
	v_permlane32_swap_b32_e32 v105, v107
	v_exp_f32_e32 v219, v219
	s_waitcnt lgkmcnt(0)
	v_mfma_f32_32x32x16_bf16 v[68:83], v[130:133], v[158:161], v[68:83]
	ds_read_b128 v[154:157], v176 offset:40960
	ds_read_b128 v[204:207], v176 offset:45056
	ds_read_b128 v[208:211], v168
	v_cvt_pk_bf16_f32 v108, v226, v1
	v_exp_f32_e32 v220, v220
	v_add_f32_e32 v212, v212, v227
	v_mfma_f32_32x32x16_bf16 v[84:99], v[150:153], v[158:161], v[84:99]
	v_cvt_pk_bf16_f32 v109, v229, v231
	v_exp_f32_e32 v221, v221
	v_add_f32_e32 v213, v213, v228
	s_waitcnt lgkmcnt(0)
	v_mfma_f32_32x32x16_bf16 v[68:83], v[154:157], v[208:211], v[68:83]
	ds_read_b128 v[130:133], v178 offset:49152
	ds_read_b128 v[150:153], v178 offset:53248
	ds_read_b128 v[158:161], v171 offset:4096
	v_cvt_pk_bf16_f32 v110, v232, v233
	v_exp_f32_e32 v222, v222
	v_add_f32_e32 v214, v214, v230
	v_mfma_f32_32x32x16_bf16 v[84:99], v[204:207], v[208:211], v[84:99]
	v_add_f32_e32 v215, v215, v111
	v_cvt_pk_bf16_f32 v111, v234, v235
	v_exp_f32_e32 v223, v223
	s_waitcnt lgkmcnt(0)
	v_mfma_f32_32x32x16_bf16 v[68:83], v[130:133], v[158:161], v[68:83]
	ds_read_b128 v[154:157], v179 offset:49152
	ds_read_b128 v[204:207], v179 offset:53248
	ds_read_b128 v[208:211], v170 offset:4096
	v_add_f32_e32 v1, v1, v213
	v_permlane32_swap_b32_e32 v108, v110
	v_add_f32_e32 v226, v226, v212
	v_mfma_f32_32x32x16_bf16 v[84:99], v[150:153], v[158:161], v[84:99]
	v_add_f32_e32 v131, v229, v214
	v_add_f32_e32 v132, v231, v215
	v_permlane32_swap_b32_e32 v109, v111
	s_waitcnt lgkmcnt(0)
	v_mfma_f32_32x32x16_bf16 v[68:83], v[154:157], v[208:211], v[68:83]
	ds_read_b128 v[150:153], v177 offset:49152
	ds_read_b128 v[158:161], v177 offset:53248
	ds_read_b128 v[212:215], v169 offset:4096
	v_add_f32_e32 v133, v232, v226
	v_add_f32_e32 v1, v233, v1
	v_cvt_pk_bf16_f32 v130, v216, v217
	v_mfma_f32_32x32x16_bf16 v[84:99], v[204:207], v[208:211], v[84:99]
	v_add_f32_e32 v226, v234, v131
	v_cvt_pk_bf16_f32 v131, v218, v219
	v_add_f32_e32 v227, v235, v132
	s_waitcnt lgkmcnt(0)
	v_mfma_f32_32x32x16_bf16 v[68:83], v[150:153], v[212:215], v[68:83]
	ds_read_b128 v[154:157], v176 offset:49152
	ds_read_b128 v[204:207], v176 offset:53248
	ds_read_b128 v[208:211], v168 offset:4096
	v_add_f32_e32 v1, v217, v1
	v_cvt_pk_bf16_f32 v132, v220, v221
	v_add_f32_e32 v216, v216, v133
	v_mfma_f32_32x32x16_bf16 v[84:99], v[158:161], v[212:215], v[84:99]
	v_cvt_pk_bf16_f32 v133, v222, v223
	v_add_f32_e32 v150, v218, v226
	v_add_f32_e32 v151, v219, v227
	s_waitcnt lgkmcnt(0)
	v_mfma_f32_32x32x16_bf16 v[68:83], v[154:157], v[208:211], v[68:83]
	v_add_f32_e32 v1, v221, v1
	v_permlane32_swap_b32_e32 v130, v132
	v_add_f32_e32 v152, v220, v216
	v_mfma_f32_32x32x16_bf16 v[84:99], v[204:207], v[208:211], v[84:99]
	v_permlane32_swap_b32_e32 v131, v133
	v_add_f32_e32 v150, v222, v150
	v_add_f32_e32 v151, v223, v151
	v_add_f32_e32 v1, v152, v1
	v_add_f32_e32 v150, v150, v151
	v_add_f32_e32 v205, v1, v150
	v_mov_b32_e32 v206, v205
	s_nop 1
	v_permlane32_swap_b32_e32 v205, v206
; #define SBAR() __builtin_amdgcn_sched_barrier(0)
; #define DMA_K(t, bf) do { if (ABL & 8) break; const char* kb_ = Kt + (size_t)(t) * KSTEP; LAS unsigned char* kd_ = Kl + (bf) * SHM_K + wid * 1024; \
;     glds16(kb_ + voffK, kd_); glds16(kb_ + 128 + voffK, kd_ + 8192); glds16(Pt + (size_t)(t) * PSTEP + voffP, kd_ + 16384); } while (0)
; #define DMA_V(t, bf) do { if (ABL & 8) break; const char* vb_ = Kt + 256 + (size_t)(t) * KSTEP; LAS unsigned char* vd_ = Vl + (bf) * SHM_V + wid * 1024; \
;     glds16(vb_ + voffV, vd_); glds16(vb_ + (size_t)32 * LDKV * 2 + voffV, vd_ + 8192); } while (0)
; #define END_STEP() do { if (!(ABL & 8)) { asm volatile("s_waitcnt vmcnt(0)" ::: "memory"); __syncthreads(); } } while (0)
; #define RESC(a) do { if (__any((a) < 1.f)) { if (hi == 0) al_l[r32] = (a); asm volatile("s_waitcnt lgkmcnt(0)" ::: "memory"); \
;     _Pragma("unroll") for (int d = 0; d < 4; ++d) _Pragma("unroll") for (int r = 0; r < 16; ++r) o[d][r] *= al_l[crow(r, hi)]; } } while (0)
; #define PV_TILE(VB, C0, C1, alC, PAR) do { s16x4 va_[8], vb_[8]; float ma_ = 0.f, mb_ = 0.f, mn_ = 0.f; VRD8(VB, 0, va_); SBAR(); \
;     PV_BLK(VB, 0, va_, vb_, C0, C1, PAR); if (PAR) { DECIDE(alC); } SBAR(); \
;     PV_BLK(VB, 1, vb_, va_, C0, C1, PAR); PV_BLK(VB, 2, va_, vb_, C0, C1, PAR); PV_BLK(VB, 3, vb_, va_, C0, C1, PAR); } while (0)
; template <int ABL> __device__ __forceinline__ void attn_unit(int b, int h, int qb, const bf16_t* Q, const bf16_t* KV, const bf16_t* KPE, bf16_t* MG, float* ssqa, LAS unsigned char* L) {
;     ...
;   for (int j = 1; j + 1 < NT; j += 2) {
;     SBAR(); QK_TILE(Kl + SHM_K, pB0, pB1, pA0, pA1, alA, true);
;     SBAR(); PAR_ONLY(pB0, pB1, alB); SBAR(); PV_TILE(Vp, pB0, pB1, alB, false);
;     RESC(alB);
;     END_STEP(); DMA_K(j + 2, 1); DMA_V(j + 1, 0);
;     SBAR(); QK_TILE(Kl, pA0, pA1, pB0, pB1, alB, true);
;     SBAR(); PAR_ONLY(pA0, pA1, alA); SBAR(); PV_TILE(Vp + SHM_V, pA0, pA1, alA, false);
;     RESC(alA);
.LBB0_760:
	ds_read_b64_tr_b16 v[150:151], v167 offset:16384
	ds_read_b64_tr_b16 v[152:153], v167 offset:18432
	ds_read_b64_tr_b16 v[154:155], v167 offset:20480
	ds_read_b64_tr_b16 v[156:157], v167 offset:22528
	ds_read_b64_tr_b16 v[158:159], v167 offset:24576
	ds_read_b64_tr_b16 v[160:161], v167 offset:26624
	ds_read_b64_tr_b16 v[208:209], v167 offset:28672
	ds_read_b64_tr_b16 v[210:211], v167 offset:30720
	v_max_f32_e32 v1, v69, v69
	v_max_f32_e32 v248, v68, v68
	v_max_f32_e32 v1, v248, v1
	v_max3_f32 v248, v70, v71, v85
	v_max3_f32 v1, v1, v84, v86
	v_max3_f32 v1, v1, v87, v72
	v_max3_f32 v248, v248, v74, v75
	v_max3_f32 v1, v1, v73, v88
	v_max3_f32 v248, v248, v90, v91
	s_waitcnt lgkmcnt(6)
	v_mfma_f32_32x32x16_bf16 v[4:19], v[100:103], v[150:153], v[4:19]
	ds_read_b64_tr_b16 v[212:213], v167 offset:16896
	ds_read_b64_tr_b16 v[214:215], v167 offset:18944
	v_max3_f32 v1, v1, v89, v76
	v_max3_f32 v248, v248, v78, v79
	v_max3_f32 v1, v1, v77, v92
	s_waitcnt lgkmcnt(6)
	v_mfma_f32_32x32x16_bf16 v[4:19], v[104:107], v[154:157], v[4:19]
	ds_read_b64_tr_b16 v[150:151], v167 offset:20992
	ds_read_b64_tr_b16 v[152:153], v167 offset:23040
	v_max3_f32 v248, v248, v94, v95
	v_max3_f32 v1, v1, v93, v80
	v_max3_f32 v248, v248, v82, v83
	s_waitcnt lgkmcnt(6)
	v_mfma_f32_32x32x16_bf16 v[4:19], v[108:111], v[158:161], v[4:19]
	ds_read_b64_tr_b16 v[154:155], v167 offset:25088
	ds_read_b64_tr_b16 v[156:157], v167 offset:27136
	v_max3_f32 v1, v1, v81, v96
	v_max3_f32 v248, v248, v98, v99
	v_max3_f32 v1, v1, v97, v248
	s_waitcnt lgkmcnt(6)
	v_mfma_f32_32x32x16_bf16 v[4:19], v[130:133], v[208:211], v[4:19]
	ds_read_b64_tr_b16 v[158:159], v167 offset:29184
	ds_read_b64_tr_b16 v[160:161], v167 offset:31232
	v_mov_b32_e32 v248, v1
	s_waitcnt lgkmcnt(6)
	v_mfma_f32_32x32x16_bf16 v[52:67], v[100:103], v[212:215], v[52:67]
	ds_read_b64_tr_b16 v[208:209], v167 offset:17408
	ds_read_b64_tr_b16 v[210:211], v167 offset:19456
	v_permlane32_swap_b32_e32 v1, v248
	v_max_f32_e32 v248, v248, v248
	v_max_f32_e32 v1, v1, v1
	v_max_f32_e32 v1, v1, v248
	s_waitcnt lgkmcnt(6)
	v_mfma_f32_32x32x16_bf16 v[52:67], v[104:107], v[150:153], v[52:67]
	ds_read_b64_tr_b16 v[212:213], v167 offset:21504
	ds_read_b64_tr_b16 v[214:215], v167 offset:23552
	v_sub_f32_e32 v248, v1, v140
	v_cmp_ge_f32_e32 vcc, s3, v248
	s_cmp_eq_u64 vcc, exec
	v_mov_b32_e32 v204, 1.0
	s_cbranch_scc0 .LBB0_769
.Lattn_back_b:
	s_waitcnt lgkmcnt(6)
	v_mfma_f32_32x32x16_bf16 v[52:67], v[108:111], v[154:157], v[52:67]
	ds_read_b64_tr_b16 v[150:151], v167 offset:25600
	ds_read_b64_tr_b16 v[152:153], v167 offset:27648
	v_sub_f32_e32 v249, v68, v140
	v_sub_f32_e32 v69, v69, v140
	v_sub_f32_e32 v70, v70, v140
	s_waitcnt lgkmcnt(6)
	v_mfma_f32_32x32x16_bf16 v[52:67], v[130:133], v[158:161], v[52:67]
	ds_read_b64_tr_b16 v[154:155], v167 offset:29696
	ds_read_b64_tr_b16 v[156:157], v167 offset:31744
	v_sub_f32_e32 v71, v71, v140
	v_sub_f32_e32 v72, v72, v140
	v_sub_f32_e32 v73, v73, v140
	s_waitcnt lgkmcnt(6)
	v_mfma_f32_32x32x16_bf16 v[36:51], v[100:103], v[208:211], v[36:51]
	ds_read_b64_tr_b16 v[158:159], v167 offset:17920
	ds_read_b64_tr_b16 v[160:161], v167 offset:19968
	v_sub_f32_e32 v74, v74, v140
	v_sub_f32_e32 v75, v75, v140
	v_sub_f32_e32 v76, v76, v140
	s_waitcnt lgkmcnt(6)
	v_mfma_f32_32x32x16_bf16 v[36:51], v[104:107], v[212:215], v[36:51]
	ds_read_b64_tr_b16 v[208:209], v167 offset:22016
	ds_read_b64_tr_b16 v[210:211], v167 offset:24064
	v_sub_f32_e32 v77, v77, v140
	v_sub_f32_e32 v78, v78, v140
	v_sub_f32_e32 v79, v79, v140
	s_waitcnt lgkmcnt(6)
	v_mfma_f32_32x32x16_bf16 v[36:51], v[108:111], v[150:153], v[36:51]
	ds_read_b64_tr_b16 v[212:213], v167 offset:26112
	ds_read_b64_tr_b16 v[214:215], v167 offset:28160
	v_sub_f32_e32 v80, v80, v140
	v_sub_f32_e32 v81, v81, v140
	v_sub_f32_e32 v82, v82, v140
	s_waitcnt lgkmcnt(6)
	v_mfma_f32_32x32x16_bf16 v[36:51], v[130:133], v[154:157], v[36:51]
	ds_read_b64_tr_b16 v[150:151], v167 offset:30208
	ds_read_b64_tr_b16 v[152:153], v167 offset:32256
	v_sub_f32_e32 v83, v83, v140
	v_exp_f32_e32 v68, v249
	s_waitcnt lgkmcnt(6)
	v_mfma_f32_32x32x16_bf16 v[20:35], v[100:103], v[158:161], v[20:35]
	s_waitcnt lgkmcnt(4)
	v_mfma_f32_32x32x16_bf16 v[20:35], v[104:107], v[208:211], v[20:35]
	s_waitcnt lgkmcnt(2)
	v_mfma_f32_32x32x16_bf16 v[20:35], v[108:111], v[212:215], v[20:35]
	s_waitcnt lgkmcnt(0)
	v_mfma_f32_32x32x16_bf16 v[20:35], v[130:133], v[150:153], v[20:35]
	v_cmp_gt_f32_e32 vcc, 1.0, v204
	s_cbranch_vccz .LBB0_764
	s_and_saveexec_b64 s[54:55], s[0:1]
	ds_write_b32 v166, v204 offset:128
	s_or_b64 exec, exec, s[54:55]
	s_waitcnt lgkmcnt(0)
	v_add_u32_e32 v1, s57, v165
	ds_read_b128 v[100:103], v1 offset:224
	ds_read_b128 v[104:107], v1 offset:192
	ds_read_b128 v[108:111], v1 offset:160
	ds_read_b128 v[130:133], v1 offset:128
	s_waitcnt lgkmcnt(3)
	v_pk_mul_f32 v[16:17], v[16:17], v[100:101]
	s_waitcnt lgkmcnt(2)
	v_pk_mul_f32 v[12:13], v[12:13], v[104:105]
	s_waitcnt lgkmcnt(1)
	v_pk_mul_f32 v[8:9], v[8:9], v[108:109]
	v_pk_mul_f32 v[18:19], v[18:19], v[102:103]
	v_pk_mul_f32 v[14:15], v[14:15], v[106:107]
	v_pk_mul_f32 v[10:11], v[10:11], v[110:111]
	s_waitcnt lgkmcnt(0)
	v_pk_mul_f32 v[6:7], v[6:7], v[132:133]
	v_pk_mul_f32 v[4:5], v[4:5], v[130:131]
	v_pk_mul_f32 v[64:65], v[64:65], v[100:101]
	v_pk_mul_f32 v[60:61], v[60:61], v[104:105]
	v_pk_mul_f32 v[56:57], v[56:57], v[108:109]
	v_pk_mul_f32 v[66:67], v[66:67], v[102:103]
	v_pk_mul_f32 v[62:63], v[62:63], v[106:107]
	v_pk_mul_f32 v[58:59], v[58:59], v[110:111]
	v_pk_mul_f32 v[54:55], v[54:55], v[132:133]
	v_pk_mul_f32 v[52:53], v[52:53], v[130:131]
	v_pk_mul_f32 v[48:49], v[48:49], v[100:101]
	v_pk_mul_f32 v[44:45], v[44:45], v[104:105]
	v_pk_mul_f32 v[40:41], v[40:41], v[108:109]
	v_pk_mul_f32 v[50:51], v[50:51], v[102:103]
	v_pk_mul_f32 v[46:47], v[46:47], v[106:107]
	v_pk_mul_f32 v[42:43], v[42:43], v[110:111]
	v_pk_mul_f32 v[38:39], v[38:39], v[132:133]
	v_pk_mul_f32 v[36:37], v[36:37], v[130:131]
	v_pk_mul_f32 v[32:33], v[32:33], v[100:101]
	v_pk_mul_f32 v[28:29], v[28:29], v[104:105]
	v_pk_mul_f32 v[24:25], v[24:25], v[108:109]
	v_pk_mul_f32 v[34:35], v[34:35], v[102:103]
	v_pk_mul_f32 v[30:31], v[30:31], v[106:107]
	v_pk_mul_f32 v[26:27], v[26:27], v[110:111]
	v_pk_mul_f32 v[22:23], v[22:23], v[132:133]
	v_pk_mul_f32 v[20:21], v[20:21], v[130:131]

; template <int G> __device__ __forceinline__ void par_gap(f32x16& C0, f32x16& C1, float& ma, float& mb, float mn) {
;     ...
;   else if constexpr (G == 4) { _Pragma("unroll") for (int r = 0; r < 8; ++r) C0[r] -= mn; }
;   else if constexpr (G == 5) { _Pragma("unroll") for (int r = 8; r < 16; ++r) C0[r] -= mn; }
;   else if constexpr (G == 6) { _Pragma("unroll") for (int r = 0; r < 8; ++r) C1[r] -= mn; }
;   else if constexpr (G == 7) { _Pragma("unroll") for (int r = 8; r < 16; ++r) C1[r] -= mn; }
;   else if constexpr (G >= 8 && G < 12) { _Pragma("unroll") for (int r = 4 * (G - 8); r < 4 * (G - 8) + 4; ++r) C0[r] = __builtin_amdgcn_exp2f(C0[r]); }
; }
.LBB0_766:
	v_exp_f32_e32 v1, v69
	v_exp_f32_e32 v112, v70
	v_exp_f32_e32 v113, v71
	v_exp_f32_e32 v110, v72
	v_exp_f32_e32 v111, v73
	v_exp_f32_e32 v108, v74
	v_exp_f32_e32 v109, v75
	v_exp_f32_e32 v106, v76
	v_exp_f32_e32 v107, v77
	v_exp_f32_e32 v104, v78
	v_exp_f32_e32 v105, v79
	v_exp_f32_e32 v102, v80
	v_exp_f32_e32 v103, v81
	v_exp_f32_e32 v100, v82
	v_exp_f32_e32 v101, v83
	v_add_f32_e32 v69, v201, v202
	v_fmac_f32_e32 v69, v2, v180
	v_add_f32_e32 v2, v205, v206
	v_fmac_f32_e32 v2, v69, v203
	s_andn2_b64 vcc, exec, s[54:55]
	s_cbranch_vccz .LBB0_770
	v_mov_b32_e32 v180, v204
	s_branch .LBB0_754

.LBB0_769:
	v_max_f32_e32 v1, v1, v1
	v_max_f32_e32 v248, v140, v140
	v_max_f32_e32 v1, v248, v1
	v_sub_f32_e32 v140, v140, v1
	v_exp_f32_e32 v204, v140
	v_mov_b32_e32 v140, v1
	s_branch .Lattn_back_b

; __global__ void __launch_bounds__(512, 2) hymba_fwd(Args args) {
	.amdhsa_kernel _Z9hymba_fwd4Args
		.amdhsa_group_segment_fixed_size 0
		.amdhsa_private_segment_fixed_size 0
		.amdhsa_kernarg_size 416
		.amdhsa_user_sgpr_count 2
		.amdhsa_user_sgpr_dispatch_ptr 0
		.amdhsa_user_sgpr_queue_ptr 0
		.amdhsa_user_sgpr_kernarg_segment_ptr 1
		.amdhsa_user_sgpr_dispatch_id 0
		.amdhsa_user_sgpr_kernarg_preload_length 0
		.amdhsa_user_sgpr_kernarg_preload_offset 0
		.amdhsa_user_sgpr_private_segment_size 0
		.amdhsa_uses_dynamic_stack 0
		.amdhsa_enable_private_segment 0
		.amdhsa_system_sgpr_workgroup_id_x 1
		.amdhsa_system_sgpr_workgroup_id_y 0
		.amdhsa_system_sgpr_workgroup_id_z 0
		.amdhsa_system_sgpr_workgroup_info 0
		.amdhsa_system_vgpr_workitem_id 0
		.amdhsa_next_free_vgpr 256
		.amdhsa_next_free_sgpr 98
		.amdhsa_accum_offset 256
		.amdhsa_reserve_vcc 1
		.amdhsa_float_round_mode_32 0
		.amdhsa_float_round_mode_16_64 0
		.amdhsa_float_denorm_mode_32 3
		.amdhsa_float_denorm_mode_16_64 3
		.amdhsa_dx10_clamp 1
		.amdhsa_ieee_mode 1
		.amdhsa_fp16_overflow 0
		.amdhsa_tg_split 0
		.amdhsa_exception_fp_ieee_invalid_op 0
		.amdhsa_exception_fp_denorm_src 0
		.amdhsa_exception_fp_ieee_div_zero 0
		.amdhsa_exception_fp_ieee_overflow 0
		.amdhsa_exception_fp_ieee_underflow 0
		.amdhsa_exception_fp_ieee_inexact 0
		.amdhsa_exception_int_div_zero 0
	.end_amdhsa_kernel

; __global__ void __launch_bounds__(512, 2) hymba_fwd(Args args) {
amdhsa.kernels:
  - .agpr_count:     0
    .args:
      - .offset:         0
        .size:           160
        .value_kind:     by_value
      - .offset:         160
        .size:           4
        .value_kind:     hidden_block_count_x
      - .offset:         164
        .size:           4
        .value_kind:     hidden_block_count_y
      - .offset:         168
        .size:           4
        .value_kind:     hidden_block_count_z
      - .offset:         172
        .size:           2
        .value_kind:     hidden_group_size_x
      - .offset:         174
        .size:           2
        .value_kind:     hidden_group_size_y
      - .offset:         176
        .size:           2
        .value_kind:     hidden_group_size_z
      - .offset:         178
        .size:           2
        .value_kind:     hidden_remainder_x
      - .offset:         180
        .size:           2
        .value_kind:     hidden_remainder_y
      - .offset:         182
        .size:           2
        .value_kind:     hidden_remainder_z
      - .offset:         200
        .size:           8
        .value_kind:     hidden_global_offset_x
      - .offset:         208
        .size:           8
        .value_kind:     hidden_global_offset_y
      - .offset:         216
        .size:           8
        .value_kind:     hidden_global_offset_z
      - .offset:         224
        .size:           2
        .value_kind:     hidden_grid_dims
      - .offset:         280
        .size:           4
        .value_kind:     hidden_dynamic_lds_size
    .group_segment_fixed_size: 0
    .kernarg_segment_align: 8
    .kernarg_segment_size: 416
    .language:       OpenCL C
    .language_version:
      - 2
      - 0
    .max_flat_workgroup_size: 512
    .name:           _Z9hymba_fwd4Args
    .private_segment_fixed_size: 0
    .sgpr_count:     104
    .sgpr_spill_count: 44
    .symbol:         _Z9hymba_fwd4Args.kd
    .uniform_work_group_size: 1
    .uses_dynamic_stack: false
    .vgpr_count:     256
    .vgpr_spill_count: 0
    .wavefront_size: 64
